# v9 + UKV GEMM walks tiles from the opposite block end (balances UQ+UKV tile counts per block)
# speedup vs baseline: 1.0023x; 1.0023x over previous
; DI int tidx() { int t = threadIdx.x; asm volatile("" : "+v"(t)); return t; }
; DI int bidx() { int b = blockIdx.x; asm volatile("" : "+s"(b)); return b; }
; DI int gdim() { int g = gridDim.x; asm volatile("" : "+s"(g)); return g; }
; template <int MODE>
; DI void gemm_phase(const bf16_t* __restrict__ A, const bf16_t* __restrict__ Bt, int M, int N, int K, const Epi& ep) {
;     ...
;     const int tid = tidx(), G = gdim(), bid = bidx();
;     const int nM = M / BM, nN = N / BM, nwg = nM * nN;
;     const int wid = tid >> 6, lane = tid & 63, wr = wid >> 2, wc = wid & 3, fr = lane & 15, fq = lane >> 4;
;     const int nt = K / BK;
;     unsigned goff0, goff1;
;     const __amdgpu_buffer_rsrc_t rsA = __builtin_amdgcn_make_buffer_rsrc((void*)A, (short)0, 0x7fffffff, 0x00020000);
;     const __amdgpu_buffer_rsrc_t rsB = __builtin_amdgcn_make_buffer_rsrc((void*)Bt, (short)0, 0x7fffffff, 0x00020000);
;     { int r_, c_; stage_rc(tid * 16, r_, c_); goff0 = (unsigned)(r_ * K + c_) * 2u; stage_rc(tid * 16 + 8192, r_, c_); goff1 = (unsigned)(r_ * K + c_) * 2u; }
;     for (int round = 0;; ++round) {
;         const int L = round * G + bid;
;         if (L >= nwg) break;
;         int wgid = L;
;         { const int q = nwg / NXCD, r = nwg % NXCD, xcd = wgid % NXCD, off = wgid / NXCD; wgid = (xcd < r ? xcd * (q + 1) : r * (q + 1) + (xcd - r) * q) + off; }
;         const int nig = WGM * nN, gid = wgid / nig, fm = gid * WGM, gsz = min(nM - fm, WGM);
;         const int pm = fm + ((wgid % nig) % gsz), pn = (wgid % nig) / gsz, brow = pm * BM, bcol = pn * BM;
.LBB0_811:
	v_mov_b32_e32 v0, v250
	s_mov_b32 s22, s96
	v_readlane_b32 s23, v252, 0
	s_nop 3
	s_sub_i32 s23, s22, s23
	s_add_i32 s23, s23, -1
	s_cmpk_gt_i32 s23, 0x307
	s_cbranch_scc1 .LBB0_850
	v_bfe_i32 v3, v0, 27, 1
	v_lshlrev_b32_e32 v1, 4, v0
	v_lshrrev_b32_e32 v3, 22, v3
	v_add_u32_e32 v3, v1, v3
	v_and_b32_e32 v3, 0xfffffc00, v3
	v_sub_u32_e32 v3, v1, v3
	s_waitcnt vmcnt(1)
	v_lshrrev_b32_e32 v4, 4, v3
	v_bitop3_b32 v4, v4, v3, 32 bitop3:0x6c
	v_ashrrev_i32_e32 v3, 31, v3
	v_ashrrev_i32_e32 v2, 31, v0
	v_lshrrev_b32_e32 v3, 26, v3
	v_lshrrev_b32_e32 v2, 26, v2
	v_add_u32_e32 v3, v4, v3
	v_add_u32_e32 v2, v0, v2
	v_ashrrev_i32_e32 v3, 6, v3
	v_ashrrev_i32_e32 v2, 6, v2
	v_mul_i32_i24_e32 v6, 64, v3
	v_lshlrev_b32_e32 v5, 3, v2
	v_lshlrev_b32_e32 v2, 5, v2
	v_sub_u32_e32 v4, v4, v6
	v_mov_b32_e32 v7, 1
	v_and_b32_e32 v5, 0x7ffff0, v5
	v_and_b32_e32 v2, 32, v2
	v_ashrrev_i16_sdwa v4, v7, sext(v4) dst_sel:DWORD dst_unused:UNUSED_PAD src0_sel:DWORD src1_sel:BYTE_0
	v_add_u32_sdwa v2, v2, sext(v4) dst_sel:DWORD dst_unused:UNUSED_PAD src0_sel:DWORD src1_sel:WORD_0
	v_add_lshl_u32 v3, v3, v5, 9
	v_lshl_add_u32 v128, v2, 1, v3
	v_add_u32_e32 v2, 0x2000, v1
	v_ashrrev_i32_e32 v3, 31, v2
	v_lshrrev_b32_e32 v3, 22, v3
	v_add_u32_e32 v3, v2, v3
	v_ashrrev_i32_e32 v3, 10, v3
	v_mul_i32_i24_e32 v4, 0x400, v3
	v_sub_u32_e32 v2, v2, v4
	v_lshrrev_b32_e32 v4, 4, v2
	v_bitop3_b32 v2, v4, v2, 32 bitop3:0x6c
	v_ashrrev_i32_e32 v5, 31, v2
	v_lshrrev_b32_e32 v5, 26, v5
	v_add_u32_e32 v5, v2, v5
	v_lshrrev_b32_e32 v6, 6, v5
	v_and_b32_e32 v5, 0xc0, v5
	v_lshlrev_b32_e32 v4, 3, v3
	v_lshlrev_b32_e32 v3, 5, v3
	v_sub_u32_e32 v2, v2, v5
	v_and_b32_e32 v4, 0x7ffff0, v4
	v_and_b32_e32 v3, 32, v3
	v_ashrrev_i16_sdwa v2, v7, sext(v2) dst_sel:DWORD dst_unused:UNUSED_PAD src0_sel:DWORD src1_sel:BYTE_0
	v_add_u32_sdwa v2, v3, sext(v2) dst_sel:DWORD dst_unused:UNUSED_PAD src0_sel:DWORD src1_sel:WORD_0
	v_add_lshl_u32 v3, v6, v4, 9
	v_lshl_add_u32 v129, v2, 1, v3
	v_and_b32_e32 v2, 15, v0
	v_lshlrev_b32_e32 v7, 2, v0
	v_and_b32_e32 v3, 48, v0
	v_lshlrev_b32_e32 v6, 6, v2
	v_and_b32_e32 v7, 32, v7
	v_readlane_b32 s0, v254, 50
	v_bitop3_b32 v6, v6, v7, v3 bitop3:0x36
	v_bfe_u32 v4, v0, 6, 2
	v_add_u32_e32 v130, s0, v1
	v_add_u32_e32 v8, s0, v6
	s_movk_i32 s0, 0x100
	v_ashrrev_i32_e32 v5, 8, v0
	v_readlane_b32 s1, v254, 51
	v_readlane_b32 s6, v254, 52
	v_readlane_b32 s7, v254, 53
	v_cmp_gt_u32_e64 s[36:37], s0, v0
	v_lshlrev_b32_e32 v0, 6, v0
	s_movk_i32 s0, 0x3c0
	v_add_u32_e32 v132, s1, v1
	v_add_u32_e32 v134, 16, v1
	v_cmp_eq_u32_e32 vcc, 1, v5
	v_add_u32_e32 v141, s6, v1
	v_add_u32_e32 v142, s7, v1
	v_lshlrev_b32_e32 v1, 12, v4
	v_lshl_or_b32 v2, v5, 6, v2
	v_lshlrev_b32_e32 v4, 7, v4
	v_lshlrev_b32_e32 v5, 13, v5
	v_and_or_b32 v0, v0, s0, v3
	v_add_u32_e32 v9, s1, v6
	v_add_u32_e32 v10, s6, v6
	v_add_u32_e32 v11, s7, v6
	v_add3_u32 v4, 16, v4, v3
	v_add_u32_e32 v6, 16, v6
	v_xad_u32 v0, v0, v7, 16
	v_or_b32_e32 v3, 0x800, v5
	v_or_b32_e32 v7, 0x1000, v5
	v_or_b32_e32 v12, 0x1800, v5
	v_mul_lo_u32 v2, v2, s35
	v_add_u32_e32 v131, 0x2000, v130
	v_add_u32_e32 v133, 0x2000, v132
	v_add_u32_e32 v135, 0x2000, v134
	v_add_u32_e32 v155, 0x4000, v134
	v_add_u32_e32 v140, 0x6000, v134
	v_add_u32_e32 v143, 0x2000, v142
	v_add_u32_e32 v144, 0xc000, v134
	v_add_u32_e32 v145, 0xe000, v134
	v_add_u32_e32 v146, v8, v1
	v_add_u32_e32 v147, v9, v1
	v_add_u32_e32 v148, v6, v5
	v_add_u32_e32 v149, v0, v3
	v_add_u32_e32 v150, v0, v7
	v_add_u32_e32 v151, v0, v12
	v_add_u32_e32 v152, v10, v1
	v_add_u32_e32 v153, v11, v1
	v_add_u32_e32 v154, v4, v2
	s_waitcnt vmcnt(0)
	s_branch .LBB0_814
